# producer-side priority in both attention loops: s_setprio 3 over each tile tail (vmcnt wait, next-tile LDS writes, global prefetch) up to the barrier, s_setprio 0 after it; on top of write-half priori
# speedup vs baseline: 1.0108x; 1.0032x over previous
; template <int D>
; __device__ __forceinline__ void attn_item(const bf16_t* Q, int qs, const bf16_t* Kp, int kst, const bf16_t* Vt, bf16_t* O, int os, const float* ck, const unsigned* nrm, int qb, unsigned char* lds) {
;     ...
;     auto tile = [&](int kt, int cur) {
;         const int k0 = kt * 64;
;         if (k0 <= qw0 + 31) {
;             const bf16_t* Kc = Ks + cur * 64 * KLD + r * KLD + h * 8;
;             const float* ckc = cks + cur * 64;
;             f32x16 st[2];
;             const float moff = (!ck && kt > 0) ? mrun : 0.f;
; #pragma unroll
;             for (int mt = 0; mt < 2; ++mt)
; #pragma unroll
;                 for (int g = 0; g < 4; ++g) {
;                     if (ck) {
;                         const f32x4 c4 = *(const f32x4*)(ckc + 32 * mt + 8 * g + 4 * h);
; #pragma unroll
;                         for (int e = 0; e < 4; ++e) st[mt][4 * g + e] = c4[e];
;                     } else {
; #pragma unroll
;                         for (int e = 0; e < 4; ++e) st[mt][4 * g + e] = -moff;
;                     }
;                 }
;             {
;                 bf16x8 kfr[2][2];
;                 kfr[0][0] = *(const bf16x8*)(Kc); kfr[0][1] = *(const bf16x8*)(Kc + 32 * KLD);
; #pragma unroll
;                 for (int ks = 0; ks < D / 16; ++ks) {
;                     const int cb = ks & 1, nb = cb ^ 1;
;                     if (ks + 1 < D / 16) { kfr[nb][0] = *(const bf16x8*)(Kc + (ks + 1) * 16); kfr[nb][1] = *(const bf16x8*)(Kc + 32 * KLD + (ks + 1) * 16); }
;                     __builtin_amdgcn_sched_barrier(0);
;                     st[0] = mfma32(kfr[cb][0], qf[ks], st[0]); st[1] = mfma32(kfr[cb][1], qf[ks], st[1]);
;                     __builtin_amdgcn_sched_barrier(0);
;                 }
;             }
;             if (k0 + 63 > qw0) {
; #pragma unroll
;                 for (int mt = 0; mt < 2; ++mt)
; #pragma unroll
;                     for (int e = 0; e < 16; ++e) {
;                         const int key = 32 * mt + (e & 3) + 8 * (e >> 2) + 4 * h;
;                         if (k0 + key > qw0 + r) st[mt][e] = -INFINITY;
;                     }
;             }
;     ...
;         if (kt + 1 < nkt) {
;             lstore(cur ^ 1, cur ^ 1);
;             if (kt + 3 < nkt) gload(cur ^ 1, kt + 3);
;         }
;         lds_barrier();
.LBB0_195:
	s_or_b64 exec, exec, s[4:5]
	s_setprio 3
	s_add_i32 s0, s11, -3
	s_cmp_ge_u32 s0, s9
	s_cbranch_scc1 .LBB0_198
	s_add_i32 s0, s11, -1
	s_cmp_ge_u32 s0, s9
	s_waitcnt vmcnt(4)
	ds_write_b128 v165, v[112:115] offset:13312
	s_waitcnt vmcnt(3)
	ds_write_b128 v166, v[116:119] offset:13312
	s_waitcnt vmcnt(2)
	ds_write_b128 v167, v[124:127] offset:13312
	s_waitcnt vmcnt(1)
	ds_write_b128 v168, v[128:131] offset:35840
	s_waitcnt vmcnt(0)
	ds_write_b128 v169, v[132:135] offset:35840
	s_cbranch_scc1 .LBB0_198
	v_add_u32_e32 v0, s88, v162
	v_subrev_u32_e32 v0, 64, v0
	v_mad_i64_i32 v[2:3], s[0:1], v0, s65, v[150:151]
	v_add_u32_e32 v0, s88, v163
	v_subrev_u32_e32 v0, 64, v0
	v_mad_i64_i32 v[4:5], s[0:1], v0, s65, v[152:153]
	v_add_u32_e32 v0, s88, v164
	v_subrev_u32_e32 v0, 64, v0
	global_load_dwordx4 v[112:115], v[2:3], off
	global_load_dwordx4 v[116:119], v[4:5], off
	v_mad_i64_i32 v[2:3], s[0:1], v0, s65, v[154:155]
	global_load_dwordx4 v[124:127], v[2:3], off
	global_load_dwordx4 v[128:131], v[156:157], off
	global_load_dwordx4 v[132:135], v[158:159], off
.LBB0_198:
	s_waitcnt lgkmcnt(0)
	s_barrier
	s_setprio 0
	s_add_i32 s0, s88, 0xffffff40
	v_cmp_le_i32_e32 vcc, s0, v171
	s_and_saveexec_b64 s[4:5], vcc
	s_cbranch_execz .LBB0_206
	ds_read_b128 v[2:5], v172 offset:13312
	ds_read_b128 v[6:9], v172 offset:13344
	ds_read_b128 v[10:13], v172 offset:19968
	ds_read_b128 v[182:185], v172 offset:20000
	v_xor_b32_e32 v48, 0x80000000, v175
	v_mov_b32_e32 v49, v48
	v_mov_b32_e32 v50, v48
	v_mov_b32_e32 v51, v48
	v_mov_b32_e32 v52, v48
	v_mov_b32_e32 v53, v48
	v_mov_b32_e32 v54, v48
	v_mov_b32_e32 v55, v48
	v_mov_b32_e32 v56, v48
	v_mov_b32_e32 v57, v48
	v_mov_b32_e32 v58, v48
	v_mov_b32_e32 v59, v48
	v_mov_b32_e32 v60, v48
	v_mov_b32_e32 v61, v48
	v_mov_b32_e32 v62, v48
	v_mov_b32_e32 v63, v48
	s_waitcnt lgkmcnt(3)
	s_nop 0
	v_mfma_f32_32x32x16_bf16 v[64:79], v[2:5], v[80:83], v[48:63]
	s_waitcnt lgkmcnt(1)
	v_mfma_f32_32x32x16_bf16 v[48:63], v[10:13], v[80:83], v[48:63]
	ds_read_b128 v[2:5], v172 offset:13376
	ds_read_b128 v[10:13], v172 offset:20032
	v_mfma_f32_32x32x16_bf16 v[64:79], v[6:9], v[84:87], v[64:79]
	s_waitcnt lgkmcnt(2)
	v_mfma_f32_32x32x16_bf16 v[48:63], v[182:185], v[84:87], v[48:63]
	ds_read_b128 v[6:9], v172 offset:13408
	ds_read_b128 v[182:185], v172 offset:20064
	s_waitcnt lgkmcnt(3)
	v_mfma_f32_32x32x16_bf16 v[64:79], v[2:5], v[88:91], v[64:79]
	s_waitcnt lgkmcnt(2)
	v_mfma_f32_32x32x16_bf16 v[48:63], v[10:13], v[88:91], v[48:63]
	ds_read_b128 v[2:5], v172 offset:13440
	ds_read_b128 v[10:13], v172 offset:20096
	s_waitcnt lgkmcnt(3)
	v_mfma_f32_32x32x16_bf16 v[64:79], v[6:9], v[92:95], v[64:79]
	s_waitcnt lgkmcnt(2)
	v_mfma_f32_32x32x16_bf16 v[48:63], v[182:185], v[92:95], v[48:63]
	ds_read_b128 v[6:9], v172 offset:13472
	ds_read_b128 v[182:185], v172 offset:20128
	s_waitcnt lgkmcnt(3)
	v_mfma_f32_32x32x16_bf16 v[64:79], v[2:5], v[96:99], v[64:79]
	s_waitcnt lgkmcnt(2)
	v_mfma_f32_32x32x16_bf16 v[48:63], v[10:13], v[96:99], v[48:63]
	s_waitcnt lgkmcnt(1)
	v_mfma_f32_32x32x16_bf16 v[64:79], v[6:9], v[100:103], v[64:79]
	s_waitcnt lgkmcnt(0)
	v_mfma_f32_32x32x16_bf16 v[48:63], v[182:185], v[100:103], v[48:63]
	s_add_i32 s0, s88, 0xffffff7f
	v_cmp_gt_i32_e32 vcc, s0, v160
	s_and_saveexec_b64 s[0:1], vcc
	s_cbranch_execz .LBB0_201
	v_add_u32_e32 v0, s88, v170
	v_add_u32_e32 v2, 0xffffff40, v0
	v_cmp_lt_i32_e32 vcc, v2, v161
	s_nop 2
	v_cndmask_b32_e32 v65, v222, v65, vcc
	v_cmp_le_i32_e32 vcc, v2, v161
	v_add_u32_e32 v2, 0xffffff42, v0
	s_nop 0
	v_cndmask_b32_e32 v64, v222, v64, vcc
	v_cmp_le_i32_e32 vcc, v2, v161
	v_add_u32_e32 v2, 0xffffff43, v0
	s_nop 0
	v_cndmask_b32_e32 v66, v222, v66, vcc
	v_cmp_le_i32_e32 vcc, v2, v161
	v_add_u32_e32 v2, 0xffffff48, v0
	s_nop 0
	v_cndmask_b32_e32 v67, v222, v67, vcc
	v_cmp_le_i32_e32 vcc, v2, v161
	v_add_u32_e32 v2, 0xffffff49, v0
	s_nop 0
	v_cndmask_b32_e32 v68, v222, v68, vcc
	v_cmp_le_i32_e32 vcc, v2, v161
	v_add_u32_e32 v2, 0xffffff4a, v0
	s_nop 0
	v_cndmask_b32_e32 v69, v222, v69, vcc
	v_cmp_le_i32_e32 vcc, v2, v161
	v_add_u32_e32 v2, 0xffffff4b, v0
	s_nop 0
	v_cndmask_b32_e32 v70, v222, v70, vcc
	v_cmp_le_i32_e32 vcc, v2, v161
	v_add_u32_e32 v2, 0xffffff50, v0
	s_nop 0
	v_cndmask_b32_e32 v71, v222, v71, vcc
	v_cmp_le_i32_e32 vcc, v2, v161
	v_add_u32_e32 v2, 0xffffff51, v0
	s_nop 0
	v_cndmask_b32_e32 v72, v222, v72, vcc
	v_cmp_le_i32_e32 vcc, v2, v161
	v_add_u32_e32 v2, 0xffffff52, v0
	s_nop 0
	v_cndmask_b32_e32 v73, v222, v73, vcc
	v_cmp_le_i32_e32 vcc, v2, v161
	v_add_u32_e32 v2, 0xffffff53, v0
	s_nop 0
	v_cndmask_b32_e32 v74, v222, v74, vcc
	v_cmp_le_i32_e32 vcc, v2, v161
	v_add_u32_e32 v2, 0xffffff58, v0
	s_nop 0
	v_cndmask_b32_e32 v75, v222, v75, vcc
	v_cmp_le_i32_e32 vcc, v2, v161
	v_add_u32_e32 v2, 0xffffff59, v0
	s_nop 0
	v_cndmask_b32_e32 v76, v222, v76, vcc
	v_cmp_le_i32_e32 vcc, v2, v161
	v_add_u32_e32 v2, 0xffffff5a, v0
	s_nop 0
	v_cndmask_b32_e32 v77, v222, v77, vcc
	v_cmp_le_i32_e32 vcc, v2, v161
	v_add_u32_e32 v2, 0xffffff5b, v0
	s_nop 0
	v_cndmask_b32_e32 v78, v222, v78, vcc
	v_cmp_le_i32_e32 vcc, v2, v161
	v_add_u32_e32 v2, 0xffffff60, v0
	s_nop 0
	v_cndmask_b32_e32 v79, v222, v79, vcc
	v_cmp_le_i32_e32 vcc, v2, v161
	v_add_u32_e32 v2, 0xffffff61, v0
	s_nop 0
	v_cndmask_b32_e32 v48, v222, v48, vcc
	v_cmp_le_i32_e32 vcc, v2, v161
	v_add_u32_e32 v2, 0xffffff62, v0
	s_nop 0
	v_cndmask_b32_e32 v49, v222, v49, vcc
	v_cmp_le_i32_e32 vcc, v2, v161
	v_add_u32_e32 v2, 0xffffff63, v0
	s_nop 0
	v_cndmask_b32_e32 v50, v222, v50, vcc
	v_cmp_le_i32_e32 vcc, v2, v161
	v_add_u32_e32 v2, 0xffffff68, v0
	s_nop 0
	v_cndmask_b32_e32 v51, v222, v51, vcc
	v_cmp_le_i32_e32 vcc, v2, v161
	v_add_u32_e32 v2, 0xffffff69, v0
	s_nop 0
	v_cndmask_b32_e32 v52, v222, v52, vcc
	v_cmp_le_i32_e32 vcc, v2, v161
	v_add_u32_e32 v2, 0xffffff6a, v0
	s_nop 0
	v_cndmask_b32_e32 v53, v222, v53, vcc
	v_cmp_le_i32_e32 vcc, v2, v161
	v_add_u32_e32 v2, 0xffffff6b, v0
	s_nop 0
	v_cndmask_b32_e32 v54, v222, v54, vcc
	v_cmp_le_i32_e32 vcc, v2, v161
	v_add_u32_e32 v2, 0xffffff70, v0
	s_nop 0
	v_cndmask_b32_e32 v55, v222, v55, vcc
	v_cmp_le_i32_e32 vcc, v2, v161
	v_add_u32_e32 v2, 0xffffff71, v0
	s_nop 0
	v_cndmask_b32_e32 v56, v222, v56, vcc
	v_cmp_le_i32_e32 vcc, v2, v161
	v_add_u32_e32 v2, 0xffffff72, v0
	s_nop 0
	v_cndmask_b32_e32 v57, v222, v57, vcc
	v_cmp_le_i32_e32 vcc, v2, v161
	v_add_u32_e32 v2, 0xffffff73, v0
	s_nop 0
	v_cndmask_b32_e32 v58, v222, v58, vcc
	v_cmp_le_i32_e32 vcc, v2, v161
	v_add_u32_e32 v2, 0xffffff78, v0
	s_nop 0
	v_cndmask_b32_e32 v59, v222, v59, vcc
	v_cmp_le_i32_e32 vcc, v2, v161
	v_add_u32_e32 v2, 0xffffff79, v0
	s_nop 0
	v_cndmask_b32_e32 v60, v222, v60, vcc
	v_cmp_le_i32_e32 vcc, v2, v161
	v_add_u32_e32 v2, 0xffffff7a, v0
	v_add_u32_e32 v0, 0xffffff7b, v0
	v_cndmask_b32_e32 v61, v222, v61, vcc
	v_cmp_le_i32_e32 vcc, v2, v161
	s_nop 1
	v_cndmask_b32_e32 v62, v222, v62, vcc
	v_cmp_le_i32_e32 vcc, v0, v161
	s_nop 1
	v_cndmask_b32_e32 v63, v222, v63, vcc

; __device__ __forceinline__ void lds_barrier() { asm volatile("s_waitcnt lgkmcnt(0)\n\ts_barrier" ::: "memory"); }
; __device__ __forceinline__ uint32_t pk2(float lo, float hi) { typedef float f2 __attribute__((ext_vector_type(2))); const f2 v = {lo, hi}; return __builtin_bit_cast(uint32_t, __builtin_convertvector(v, bf16x2_t)); }
; template <int D>
; __device__ __forceinline__ void attn_item(const bf16_t* Q, int qs, const bf16_t* Kp, int kst, const bf16_t* Vt, bf16_t* O, int os, const float* ck, const unsigned* nrm, int qb, unsigned char* lds) {
;     ...
;         if (kt + 1 < nkt) {
;             lstore(cur ^ 1, cur ^ 1);
;             if (kt + 3 < nkt) gload(cur ^ 1, kt + 3);
;         }
;         lds_barrier();
;     ...
; #pragma unroll 1
;     for (int kt = kts; kt < nkt; kt += 2) { tile(kt, 0); tile(kt + 1, 1); }
;     const float l = lsum + __shfl_xor(lsum, 32);
;     const float inv = 1.f / l;
; #pragma unroll
;     for (int dt = 0; dt < 2; ++dt)
; #pragma unroll
;         for (int g = 0; g < 4; ++g) {
;             u32x2 w = {pk2(ot[dt][4 * g] * inv, ot[dt][4 * g + 1] * inv), pk2(ot[dt][4 * g + 2] * inv, ot[dt][4 * g + 3] * inv)};
;             *(u32x2*)(O + (size_t)(qw0 + r) * os + 32 * dt + 8 * g + 4 * h) = w;
;         }
.LBB0_206:
	s_or_b64 exec, exec, s[4:5]
	s_setprio 3
	s_add_i32 s0, s11, -4
	s_cmp_ge_u32 s0, s10
	s_cbranch_scc1 .LBB0_209
	s_cmp_ge_u32 s11, s9
	s_waitcnt vmcnt(4)
	ds_write_b128 v165, v[104:107]
	s_waitcnt vmcnt(3)
	ds_write_b128 v166, v[108:111]
	s_waitcnt vmcnt(2)
	ds_write_b128 v167, v[136:139]
	s_waitcnt vmcnt(1)
	ds_write_b128 v168, v[120:123] offset:26624
	s_waitcnt vmcnt(0)
	ds_write_b128 v169, v[140:143] offset:26624
	s_cbranch_scc1 .LBB0_209
	v_add_u32_e32 v0, s88, v162
	v_mad_i64_i32 v[2:3], s[0:1], v0, s65, v[150:151]
	v_add_u32_e32 v0, s88, v163
	v_mad_i64_i32 v[4:5], s[0:1], v0, s65, v[152:153]
	v_add_u32_e32 v0, s88, v164
	global_load_dwordx4 v[104:107], v[2:3], off
	global_load_dwordx4 v[108:111], v[4:5], off
	v_mad_i64_i32 v[2:3], s[0:1], v0, s65, v[154:155]
	s_lshl_b64 s[0:1], s[88:89], 1
	s_nop 0
	v_lshl_add_u64 v[4:5], v[146:147], 0, s[0:1]
	global_load_dwordx4 v[136:139], v[2:3], off
	global_load_dwordx4 v[120:123], v[4:5], off
	v_lshl_add_u64 v[2:3], v[148:149], 0, s[0:1]
	global_load_dwordx4 v[140:143], v[2:3], off
.LBB0_209:
	s_waitcnt lgkmcnt(0)
	s_barrier
	s_setprio 0
	s_addk_i32 s88, 0x80
	s_add_i32 s0, s11, 2
	s_mov_b64 s[4:5], 0x100
	s_add_i32 s1, s11, -2
	v_lshl_add_u64 v[156:157], v[156:157], 0, s[4:5]
	s_cmp_lt_u32 s1, s9
	s_mov_b64 s[92:93], 0x100
	v_lshl_add_u64 v[158:159], v[158:159], 0, s[4:5]
	s_cbranch_scc1 .LBB0_187
	v_and_b32_e32 v2, 64, v228
	v_xor_b32_e32 v0, 32, v228
	v_add_u32_e32 v2, 64, v2
	v_cmp_lt_i32_e32 vcc, v0, v2
	s_nop 1
	v_cndmask_b32_e32 v0, v228, v0, vcc
	v_lshlrev_b32_e32 v0, 2, v0
	ds_bpermute_b32 v0, v0, v174
	s_waitcnt lgkmcnt(0)
	v_add_f32_e32 v2, v174, v0
	v_div_scale_f32 v3, s[0:1], v2, v2, 1.0
	v_rcp_f32_e32 v4, v3
	v_div_scale_f32 v5, vcc, 1.0, v2, 1.0
	v_lshlrev_b32_e32 v0, 1, v170
	v_fma_f32 v6, -v3, v4, 1.0
	v_fmac_f32_e32 v4, v6, v4
	v_mul_f32_e32 v6, v5, v4
	v_fma_f32 v7, -v3, v6, v5
	v_fmac_f32_e32 v6, v7, v4
	v_fma_f32 v3, -v3, v6, v5
	v_div_fmas_f32 v3, v3, v4, v6
	v_div_fixup_f32 v2, v3, v2, 1.0
	v_pk_mul_f32 v[6:7], v[32:33], v[2:3] op_sel_hi:[1,0]
	v_pk_mul_f32 v[8:9], v[34:35], v[2:3] op_sel_hi:[1,0]
	v_lshl_add_u64 v[4:5], v[144:145], 0, v[0:1]
	v_cvt_pk_bf16_f32 v6, v6, v7
	v_cvt_pk_bf16_f32 v7, v8, v9
	global_store_dwordx2 v[4:5], v[6:7], off
	v_pk_mul_f32 v[6:7], v[36:37], v[2:3] op_sel_hi:[1,0]
	v_pk_mul_f32 v[8:9], v[38:39], v[2:3] op_sel_hi:[1,0]
	v_cvt_pk_bf16_f32 v6, v6, v7
	v_cvt_pk_bf16_f32 v7, v8, v9
	global_store_dwordx2 v[4:5], v[6:7], off offset:16
	v_pk_mul_f32 v[6:7], v[40:41], v[2:3] op_sel_hi:[1,0]
	v_pk_mul_f32 v[8:9], v[42:43], v[2:3] op_sel_hi:[1,0]
	v_cvt_pk_bf16_f32 v6, v6, v7
	v_cvt_pk_bf16_f32 v7, v8, v9
	global_store_dwordx2 v[4:5], v[6:7], off offset:32
	v_pk_mul_f32 v[6:7], v[44:45], v[2:3] op_sel_hi:[1,0]
	v_pk_mul_f32 v[8:9], v[46:47], v[2:3] op_sel_hi:[1,0]
	v_cvt_pk_bf16_f32 v6, v6, v7
	v_cvt_pk_bf16_f32 v7, v8, v9
	global_store_dwordx2 v[4:5], v[6:7], off offset:48
	v_pk_mul_f32 v[6:7], v[16:17], v[2:3] op_sel_hi:[1,0]
	v_pk_mul_f32 v[8:9], v[18:19], v[2:3] op_sel_hi:[1,0]
	v_cvt_pk_bf16_f32 v6, v6, v7
	v_cvt_pk_bf16_f32 v7, v8, v9
	global_store_dwordx2 v[4:5], v[6:7], off offset:64
	v_pk_mul_f32 v[6:7], v[20:21], v[2:3] op_sel_hi:[1,0]
	v_pk_mul_f32 v[8:9], v[22:23], v[2:3] op_sel_hi:[1,0]
	v_cvt_pk_bf16_f32 v6, v6, v7
	v_cvt_pk_bf16_f32 v7, v8, v9
	global_store_dwordx2 v[4:5], v[6:7], off offset:80
	v_pk_mul_f32 v[6:7], v[24:25], v[2:3] op_sel_hi:[1,0]
	v_pk_mul_f32 v[8:9], v[26:27], v[2:3] op_sel_hi:[1,0]
	v_cvt_pk_bf16_f32 v6, v6, v7
	v_cvt_pk_bf16_f32 v7, v8, v9
	global_store_dwordx2 v[4:5], v[6:7], off offset:96
	v_pk_mul_f32 v[6:7], v[28:29], v[2:3] op_sel_hi:[1,0]
	v_pk_mul_f32 v[2:3], v[30:31], v[2:3] op_sel_hi:[1,0]
	v_cvt_pk_bf16_f32 v6, v6, v7
	v_cvt_pk_bf16_f32 v7, v2, v3
	global_store_dwordx2 v[4:5], v[6:7], off offset:112
	s_mov_b64 s[0:1], 0

; __device__ __forceinline__ void lds_barrier() { asm volatile("s_waitcnt lgkmcnt(0)\n\ts_barrier" ::: "memory"); }
; template <int D>
; __device__ __forceinline__ void attn_item(const bf16_t* Q, int qs, const bf16_t* Kp, int kst, const bf16_t* Vt, bf16_t* O, int os, const float* ck, const unsigned* nrm, int qb, unsigned char* lds) {
;     ...
;     auto gload = [&](int st, int kt) {
;         const int k0 = kt * 64;
; #pragma unroll
;         for (int i = 0; i < NKP; ++i) { const int id = tid + 256 * i, row = id / KPR, c = id % KPR; rk[st][i] = *(const u32x4*)(Kp + (size_t)(k0 + row) * kst + c * 8); }
; #pragma unroll
;         for (int i = 0; i < 2; ++i) { const int id = tid + 256 * i, row = id >> 3, c = id & 7; rv[st][i] = *(const u32x4*)(Vt + (size_t)row * TH + k0 + c * 8); }
;         if (ck && tid < 64) rck[st] = ck[k0 + tid];
;     ...
;     auto lstore = [&](int st, int buf) {
; #pragma unroll
;         for (int i = 0; i < NKP; ++i) { const int id = tid + 256 * i, row = id / KPR, c = id % KPR; *(u32x4*)(Ks + buf * 64 * KLD + row * KLD + c * 8) = rk[st][i]; }
; #pragma unroll
;         for (int i = 0; i < 2; ++i) { const int id = tid + 256 * i, row = id >> 3, c = id & 7; *(u32x4*)(Vs + buf * 64 * 72 + row * 72 + c * 8) = rv[st][i]; }
;         if (ck && tid < 64) cks[buf * 64 + tid] = coff - rck[st];
;     };
;     ...
;         if (kt + 1 < nkt) {
;             lstore(cur ^ 1, cur ^ 1);
;             if (kt + 3 < nkt) gload(cur ^ 1, kt + 3);
;         }
;         lds_barrier();
.LBB0_240:
	s_or_b64 exec, exec, s[6:7]
	s_setprio 3
	s_add_i32 s0, s9, -3
	s_cmp_ge_i32 s0, s10
	s_cbranch_scc1 .LBB0_247
	s_waitcnt vmcnt(3)
	ds_write_b128 v146, v[104:107] offset:9216
	s_waitcnt vmcnt(2)
	ds_write_b128 v147, v[108:111] offset:9216
	s_waitcnt vmcnt(1)
	ds_write_b128 v148, v[120:123] offset:27648
	s_waitcnt vmcnt(0)
	ds_write_b128 v149, v[124:127] offset:27648
	s_and_saveexec_b64 s[0:1], s[40:41]
	v_sub_f32_e32 v0, v131, v144
	ds_write_b32 v150, v0 offset:37120
	s_or_b64 exec, exec, s[0:1]
	s_add_i32 s0, s9, -1
	s_cmp_ge_i32 s0, s10
	s_cbranch_scc1 .LBB0_247
	s_add_i32 s0, s8, 0xc0
	v_add_u32_e32 v0, s0, v142
	s_ashr_i32 s1, s0, 31
	v_mad_i64_i32 v[2:3], s[6:7], v0, s60, v[132:133]
	v_add_u32_e32 v0, s0, v143
	s_lshl_b64 s[0:1], s[0:1], 1
	v_mad_i64_i32 v[4:5], s[6:7], v0, s60, v[134:135]
	global_load_dwordx4 v[104:107], v[2:3], off
	global_load_dwordx4 v[108:111], v[4:5], off
	v_lshl_add_u64 v[2:3], v[136:137], 0, s[0:1]
	v_lshl_add_u64 v[4:5], v[138:139], 0, s[0:1]
	global_load_dwordx4 v[120:123], v[2:3], off
	global_load_dwordx4 v[124:127], v[4:5], off
	s_and_saveexec_b64 s[0:1], s[40:41]
	s_cbranch_execz .LBB0_246
	v_add_u32_e32 v0, s8, v130
	v_add_u32_e32 v2, 0xc0, v0
	v_ashrrev_i32_e32 v3, 31, v2
	v_lshl_add_u64 v[2:3], v[2:3], 2, s[4:5]
	global_load_dword v144, v[2:3], off

; __device__ __forceinline__ f32x16 mfma32(bf16x8 a, bf16x8 b, f32x16 c) { return __builtin_amdgcn_mfma_f32_32x32x16_bf16(a, b, c, 0, 0, 0); }
; template <int D>
; __device__ __forceinline__ void attn_item(const bf16_t* Q, int qs, const bf16_t* Kp, int kst, const bf16_t* Vt, bf16_t* O, int os, const float* ck, const unsigned* nrm, int qb, unsigned char* lds) {
;     ...
;     auto tile = [&](int kt, int cur) {
;         const int k0 = kt * 64;
;         if (k0 <= qw0 + 31) {
;             const bf16_t* Kc = Ks + cur * 64 * KLD + r * KLD + h * 8;
;             const float* ckc = cks + cur * 64;
;             f32x16 st[2];
;             const float moff = (!ck && kt > 0) ? mrun : 0.f;
; #pragma unroll
;             for (int mt = 0; mt < 2; ++mt)
; #pragma unroll
;                 for (int g = 0; g < 4; ++g) {
;                     if (ck) {
;                         const f32x4 c4 = *(const f32x4*)(ckc + 32 * mt + 8 * g + 4 * h);
; #pragma unroll
;                         for (int e = 0; e < 4; ++e) st[mt][4 * g + e] = c4[e];
;                     } else {
; #pragma unroll
;                         for (int e = 0; e < 4; ++e) st[mt][4 * g + e] = -moff;
;                     }
;                 }
;             {
;                 bf16x8 kfr[2][2];
;                 kfr[0][0] = *(const bf16x8*)(Kc); kfr[0][1] = *(const bf16x8*)(Kc + 32 * KLD);
; #pragma unroll
;                 for (int ks = 0; ks < D / 16; ++ks) {
;                     const int cb = ks & 1, nb = cb ^ 1;
;                     if (ks + 1 < D / 16) { kfr[nb][0] = *(const bf16x8*)(Kc + (ks + 1) * 16); kfr[nb][1] = *(const bf16x8*)(Kc + 32 * KLD + (ks + 1) * 16); }
;                     __builtin_amdgcn_sched_barrier(0);
;                     st[0] = mfma32(kfr[cb][0], qf[ks], st[0]); st[1] = mfma32(kfr[cb][1], qf[ks], st[1]);
;                     __builtin_amdgcn_sched_barrier(0);
;                 }
;             }
;             if (k0 + 63 > qw0) {
; #pragma unroll
;                 for (int mt = 0; mt < 2; ++mt)
; #pragma unroll
;                     for (int e = 0; e < 16; ++e) {
;                         const int key = 32 * mt + (e & 3) + 8 * (e >> 2) + 4 * h;
;                         if (k0 + key > qw0 + r) st[mt][e] = -INFINITY;
;                     }
;             }
.LBB0_247:
	s_waitcnt lgkmcnt(0)
	s_barrier
	s_setprio 0
	s_add_i32 s0, s8, 64
	v_cmp_le_i32_e32 vcc, s0, v153
	s_and_saveexec_b64 s[6:7], vcc
	s_cbranch_execz .LBB0_257
	ds_read_b128 v[64:67], v155 offset:37120
	ds_read_b128 v[68:71], v155 offset:37152
	ds_read_b128 v[72:75], v155 offset:37184
	ds_read_b128 v[76:79], v155 offset:37216
	ds_read_b128 v[48:51], v155 offset:37248
	ds_read_b128 v[52:55], v155 offset:37280
	ds_read_b128 v[56:59], v155 offset:37312
	ds_read_b128 v[60:63], v155 offset:37344
	ds_read_b128 v[2:5], v154 offset:9216
	ds_read_b128 v[6:9], v154 offset:9248
	ds_read_b128 v[10:13], v154 offset:13824
	ds_read_b128 v[158:161], v154 offset:13856
	s_waitcnt lgkmcnt(3)
	v_mfma_f32_32x32x16_bf16 v[64:79], v[2:5], v[80:83], v[64:79]
	s_waitcnt lgkmcnt(1)
	v_mfma_f32_32x32x16_bf16 v[48:63], v[10:13], v[80:83], v[48:63]
	ds_read_b128 v[2:5], v154 offset:9280
	ds_read_b128 v[10:13], v154 offset:13888
	v_mfma_f32_32x32x16_bf16 v[64:79], v[6:9], v[84:87], v[64:79]
	s_waitcnt lgkmcnt(2)
	v_mfma_f32_32x32x16_bf16 v[48:63], v[158:161], v[84:87], v[48:63]
	ds_read_b128 v[6:9], v154 offset:9312
	ds_read_b128 v[158:161], v154 offset:13920
	s_waitcnt lgkmcnt(3)
	v_mfma_f32_32x32x16_bf16 v[64:79], v[2:5], v[88:91], v[64:79]
	s_waitcnt lgkmcnt(2)
	v_mfma_f32_32x32x16_bf16 v[48:63], v[10:13], v[88:91], v[48:63]
	s_waitcnt lgkmcnt(1)
	v_mfma_f32_32x32x16_bf16 v[64:79], v[6:9], v[92:95], v[64:79]
	s_waitcnt lgkmcnt(0)
	v_mfma_f32_32x32x16_bf16 v[48:63], v[158:161], v[92:95], v[48:63]
	s_add_i32 s0, s8, 0x7f
	v_cmp_gt_i32_e32 vcc, s0, v140
	s_and_saveexec_b64 s[0:1], vcc
	s_cbranch_execz .LBB0_250
	v_add_u32_e32 v0, s8, v151
	v_add_u32_e32 v2, 64, v0
	v_cmp_lt_i32_e32 vcc, v2, v141
	s_nop 2
	v_cndmask_b32_e32 v65, v222, v65, vcc
	v_cmp_le_i32_e32 vcc, v2, v141
	v_add_u32_e32 v2, 0x42, v0
	s_nop 0
	v_cndmask_b32_e32 v64, v222, v64, vcc
	v_cmp_le_i32_e32 vcc, v2, v141
	v_add_u32_e32 v2, 0x43, v0
	s_nop 0
	v_cndmask_b32_e32 v66, v222, v66, vcc
	v_cmp_le_i32_e32 vcc, v2, v141
	v_add_u32_e32 v2, 0x48, v0
	s_nop 0
	v_cndmask_b32_e32 v67, v222, v67, vcc
	v_cmp_le_i32_e32 vcc, v2, v141
	v_add_u32_e32 v2, 0x49, v0
	s_nop 0
	v_cndmask_b32_e32 v68, v222, v68, vcc
	v_cmp_le_i32_e32 vcc, v2, v141
	v_add_u32_e32 v2, 0x4a, v0
	s_nop 0
	v_cndmask_b32_e32 v69, v222, v69, vcc
	v_cmp_le_i32_e32 vcc, v2, v141
	v_add_u32_e32 v2, 0x4b, v0
	s_nop 0
	v_cndmask_b32_e32 v70, v222, v70, vcc
	v_cmp_le_i32_e32 vcc, v2, v141
	v_add_u32_e32 v2, 0x50, v0
	s_nop 0
	v_cndmask_b32_e32 v71, v222, v71, vcc
	v_cmp_le_i32_e32 vcc, v2, v141
	v_add_u32_e32 v2, 0x51, v0
	s_nop 0
	v_cndmask_b32_e32 v72, v222, v72, vcc
	v_cmp_le_i32_e32 vcc, v2, v141
	v_add_u32_e32 v2, 0x52, v0
	s_nop 0
	v_cndmask_b32_e32 v73, v222, v73, vcc
	v_cmp_le_i32_e32 vcc, v2, v141
	v_add_u32_e32 v2, 0x53, v0
	s_nop 0
	v_cndmask_b32_e32 v74, v222, v74, vcc
	v_cmp_le_i32_e32 vcc, v2, v141
	v_add_u32_e32 v2, 0x58, v0
	s_nop 0
	v_cndmask_b32_e32 v75, v222, v75, vcc
	v_cmp_le_i32_e32 vcc, v2, v141
	v_add_u32_e32 v2, 0x59, v0
	s_nop 0
	v_cndmask_b32_e32 v76, v222, v76, vcc
	v_cmp_le_i32_e32 vcc, v2, v141
	v_add_u32_e32 v2, 0x5a, v0
	s_nop 0
	v_cndmask_b32_e32 v77, v222, v77, vcc
	v_cmp_le_i32_e32 vcc, v2, v141
	v_add_u32_e32 v2, 0x5b, v0
	s_nop 0
	v_cndmask_b32_e32 v78, v222, v78, vcc
	v_cmp_le_i32_e32 vcc, v2, v141
	v_add_u32_e32 v2, 0x60, v0
	s_nop 0
	v_cndmask_b32_e32 v79, v222, v79, vcc
	v_cmp_le_i32_e32 vcc, v2, v141
	v_add_u32_e32 v2, 0x61, v0
	s_nop 0
	v_cndmask_b32_e32 v48, v222, v48, vcc
	v_cmp_le_i32_e32 vcc, v2, v141
	v_add_u32_e32 v2, 0x62, v0
	s_nop 0
	v_cndmask_b32_e32 v49, v222, v49, vcc
	v_cmp_le_i32_e32 vcc, v2, v141
	v_add_u32_e32 v2, 0x63, v0
	s_nop 0
	v_cndmask_b32_e32 v50, v222, v50, vcc
	v_cmp_le_i32_e32 vcc, v2, v141
	v_add_u32_e32 v2, 0x68, v0
	s_nop 0
	v_cndmask_b32_e32 v51, v222, v51, vcc
	v_cmp_le_i32_e32 vcc, v2, v141
	v_add_u32_e32 v2, 0x69, v0
	s_nop 0
	v_cndmask_b32_e32 v52, v222, v52, vcc
	v_cmp_le_i32_e32 vcc, v2, v141
	v_add_u32_e32 v2, 0x6a, v0
	s_nop 0
	v_cndmask_b32_e32 v53, v222, v53, vcc
	v_cmp_le_i32_e32 vcc, v2, v141
	v_add_u32_e32 v2, 0x6b, v0
	s_nop 0
	v_cndmask_b32_e32 v54, v222, v54, vcc
	v_cmp_le_i32_e32 vcc, v2, v141
	v_add_u32_e32 v2, 0x70, v0
	s_nop 0
	v_cndmask_b32_e32 v55, v222, v55, vcc
	v_cmp_le_i32_e32 vcc, v2, v141
	v_add_u32_e32 v2, 0x71, v0
	s_nop 0
	v_cndmask_b32_e32 v56, v222, v56, vcc
	v_cmp_le_i32_e32 vcc, v2, v141
	v_add_u32_e32 v2, 0x72, v0
	s_nop 0
	v_cndmask_b32_e32 v57, v222, v57, vcc
	v_cmp_le_i32_e32 vcc, v2, v141
	v_add_u32_e32 v2, 0x73, v0
	s_nop 0
	v_cndmask_b32_e32 v58, v222, v58, vcc
	v_cmp_le_i32_e32 vcc, v2, v141
	v_add_u32_e32 v2, 0x78, v0
	s_nop 0
	v_cndmask_b32_e32 v59, v222, v59, vcc
	v_cmp_le_i32_e32 vcc, v2, v141
	v_add_u32_e32 v2, 0x79, v0
	s_nop 0
	v_cndmask_b32_e32 v60, v222, v60, vcc
	v_cmp_le_i32_e32 vcc, v2, v141
	v_add_u32_e32 v2, 0x7a, v0
	v_add_u32_e32 v0, 0x7b, v0
	v_cndmask_b32_e32 v61, v222, v61, vcc
	v_cmp_le_i32_e32 vcc, v2, v141
	s_nop 1
	v_cndmask_b32_e32 v62, v222, v62, vcc
	v_cmp_le_i32_e32 vcc, v0, v141
	s_nop 1
	v_cndmask_b32_e32 v63, v222, v63, vcc

; __device__ __forceinline__ void lds_barrier() { asm volatile("s_waitcnt lgkmcnt(0)\n\ts_barrier" ::: "memory"); }
; template <int D>
; __device__ __forceinline__ void attn_item(const bf16_t* Q, int qs, const bf16_t* Kp, int kst, const bf16_t* Vt, bf16_t* O, int os, const float* ck, const unsigned* nrm, int qb, unsigned char* lds) {
;     ...
;     auto gload = [&](int st, int kt) {
;         const int k0 = kt * 64;
; #pragma unroll
;         for (int i = 0; i < NKP; ++i) { const int id = tid + 256 * i, row = id / KPR, c = id % KPR; rk[st][i] = *(const u32x4*)(Kp + (size_t)(k0 + row) * kst + c * 8); }
; #pragma unroll
;         for (int i = 0; i < 2; ++i) { const int id = tid + 256 * i, row = id >> 3, c = id & 7; rv[st][i] = *(const u32x4*)(Vt + (size_t)row * TH + k0 + c * 8); }
;         if (ck && tid < 64) rck[st] = ck[k0 + tid];
;     ...
;     auto lstore = [&](int st, int buf) {
; #pragma unroll
;         for (int i = 0; i < NKP; ++i) { const int id = tid + 256 * i, row = id / KPR, c = id % KPR; *(u32x4*)(Ks + buf * 64 * KLD + row * KLD + c * 8) = rk[st][i]; }
; #pragma unroll
;         for (int i = 0; i < 2; ++i) { const int id = tid + 256 * i, row = id >> 3, c = id & 7; *(u32x4*)(Vs + buf * 64 * 72 + row * 72 + c * 8) = rv[st][i]; }
;         if (ck && tid < 64) cks[buf * 64 + tid] = coff - rck[st];
;     };
;     ...
;         if (kt + 1 < nkt) {
;             lstore(cur ^ 1, cur ^ 1);
;             if (kt + 3 < nkt) gload(cur ^ 1, kt + 3);
;         }
;         lds_barrier();
.LBB0_257:
	s_or_b64 exec, exec, s[6:7]
	s_setprio 3
	s_add_i32 s0, s9, -4
	s_cmp_ge_i32 s0, s11
	s_cbranch_scc1 .LBB0_264
	s_waitcnt vmcnt(3)
	ds_write_b128 v146, v[96:99]
	s_waitcnt vmcnt(2)
	ds_write_b128 v147, v[100:103]
	s_waitcnt vmcnt(1)
	ds_write_b128 v148, v[112:115] offset:18432
	s_waitcnt vmcnt(0)
	ds_write_b128 v149, v[116:119] offset:18432
	s_and_saveexec_b64 s[0:1], s[40:41]
	v_sub_f32_e32 v0, v131, v145
	ds_write_b32 v150, v0 offset:36864
	s_or_b64 exec, exec, s[0:1]
	s_cmp_ge_i32 s9, s10
	s_cbranch_scc1 .LBB0_264
	s_add_i32 s0, s8, 0x100
	v_add_u32_e32 v0, s0, v142
	s_ashr_i32 s1, s0, 31
	v_mad_i64_i32 v[2:3], s[6:7], v0, s60, v[132:133]
	v_add_u32_e32 v0, s0, v143
	s_lshl_b64 s[0:1], s[0:1], 1
	v_mad_i64_i32 v[4:5], s[6:7], v0, s60, v[134:135]
	global_load_dwordx4 v[96:99], v[2:3], off
	global_load_dwordx4 v[100:103], v[4:5], off
	v_lshl_add_u64 v[2:3], v[136:137], 0, s[0:1]
	v_lshl_add_u64 v[4:5], v[138:139], 0, s[0:1]
	global_load_dwordx4 v[112:115], v[2:3], off
	global_load_dwordx4 v[116:119], v[4:5], off
	s_and_saveexec_b64 s[0:1], s[40:41]
	s_cbranch_execz .LBB0_263
	v_add_u32_e32 v0, s8, v130
	v_add_u32_e32 v2, 0x100, v0
	v_ashrrev_i32_e32 v3, 31, v2
	v_lshl_add_u64 v[2:3], v[2:3], 2, s[4:5]
	global_load_dword v145, v[2:3], off

; __device__ __forceinline__ void lds_barrier() { asm volatile("s_waitcnt lgkmcnt(0)\n\ts_barrier" ::: "memory"); }
; template <int D>
; __device__ __forceinline__ void attn_item(const bf16_t* Q, int qs, const bf16_t* Kp, int kst, const bf16_t* Vt, bf16_t* O, int os, const float* ck, const unsigned* nrm, int qb, unsigned char* lds) {
;     ...
;         lds_barrier();
;     ...
;     for (int kt = kts; kt < nkt; kt += 2) { tile(kt, 0); tile(kt + 1, 1); }
.LBB0_264:
	s_waitcnt lgkmcnt(0)
	s_barrier
	s_setprio 0
	s_addk_i32 s8, 0x80
	s_add_i32 s0, s9, 2
	s_add_i32 s1, s9, -2
	s_cmp_lt_i32 s1, s10
	s_cbranch_scc1 .LBB0_230
	v_mov_b32_e32 v48, v151
	s_branch .LBB0_135
